# ret_scan: exact counted vmcnt waits (per step-index case) instead of vmcnt(0)/ladders so the 2-3 step prefetch distance is real
# speedup vs baseline: 1.0306x; 1.0005x over previous
.LBB0_190:
	v_lshl_add_u32 v81, v83, 2, v147
	s_waitcnt lgkmcnt(0)
	s_barrier
	ds_read_b128 v[170:173], v81
	ds_read_b128 v[174:177], v81 offset:256
	ds_read_b128 v[178:181], v81 offset:512
	ds_read_b128 v[182:185], v81 offset:768
	ds_read_b128 v[186:189], v81 offset:1024
	ds_read_b128 v[190:193], v81 offset:1280
	ds_read_b128 v[194:197], v81 offset:1536
	ds_read_b128 v[198:201], v81 offset:1792
	ds_read_b128 v[212:215], v81 offset:64
	ds_read_b128 v[216:219], v81 offset:320
	ds_read_b128 v[220:223], v81 offset:576
	ds_read_b128 v[224:227], v81 offset:832
	ds_read_b128 v[228:231], v81 offset:1088
	ds_read_b128 v[232:235], v81 offset:1344
	ds_read_b128 v[236:239], v81 offset:1600
	ds_read_b128 v[240:243], v81 offset:1856
	s_mov_b32 s4, 0xa180000
	v_lshl_add_u64 v[88:89], v[88:89], 0, s[82:83]
	v_lshl_add_u64 v[86:87], v[86:87], 0, s[82:83]
	v_lshl_add_u64 v[90:91], v[90:91], 0, s[82:83]
	s_waitcnt lgkmcnt(14)
	v_pk_add_f32 v[72:73], v[172:173], v[176:177]
	s_waitcnt lgkmcnt(14)
	v_pk_add_f32 v[70:71], v[170:171], v[174:175]
	v_lshl_add_u64 v[92:93], v[92:93], 0, s[74:75]
	s_mov_b32 s22, s23
	s_waitcnt lgkmcnt(13)
	v_pk_add_f32 v[72:73], v[72:73], v[180:181]
	s_waitcnt lgkmcnt(13)
	v_pk_add_f32 v[70:71], v[70:71], v[178:179]
	s_waitcnt lgkmcnt(12)
	v_pk_add_f32 v[72:73], v[72:73], v[184:185]
	s_waitcnt lgkmcnt(12)
	v_pk_add_f32 v[70:71], v[70:71], v[182:183]
	s_waitcnt lgkmcnt(11)
	v_pk_add_f32 v[72:73], v[72:73], v[188:189]
	s_waitcnt lgkmcnt(11)
	v_pk_add_f32 v[70:71], v[70:71], v[186:187]
	s_waitcnt lgkmcnt(10)
	v_pk_add_f32 v[72:73], v[72:73], v[192:193]
	s_waitcnt lgkmcnt(10)
	v_pk_add_f32 v[70:71], v[70:71], v[190:191]
	s_waitcnt lgkmcnt(9)
	v_pk_add_f32 v[72:73], v[72:73], v[196:197]
	s_waitcnt lgkmcnt(9)
	v_pk_add_f32 v[70:71], v[70:71], v[194:195]
	s_waitcnt lgkmcnt(8)
	v_pk_add_f32 v[66:67], v[70:71], v[198:199]
	s_nop 0
	v_fmamk_f32 v66, v66, 0x3c000000, v169
	v_cmp_gt_f32_e32 vcc, s57, v66
	v_mul_f32_e32 v70, 0x4b800000, v66
	s_waitcnt lgkmcnt(8)
	v_pk_add_f32 v[68:69], v[72:73], v[200:201]
	v_cndmask_b32_e32 v66, v66, v70, vcc
	v_rsq_f32_e32 v66, v66
	s_nop 0
	v_mul_f32_e32 v70, 0x45800000, v66
	v_cndmask_b32_e32 v66, v66, v70, vcc
	v_mul_f32_e32 v62, v62, v66
	v_lshlrev_b32_e32 v66, 2, v121
	v_mul_lo_u32 v70, v120, s62
	v_add3_u32 v70, v115, v66, v70
	v_fmamk_f32 v66, v67, 0x3c000000, v169
	v_cmp_gt_f32_e32 vcc, s57, v66
	v_mul_f32_e32 v67, 0x4b800000, v66
	s_nop 0
	v_cndmask_b32_e32 v66, v66, v67, vcc
	v_rsq_f32_e32 v66, v66
	s_nop 0
	v_mul_f32_e32 v67, 0x45800000, v66
	v_cndmask_b32_e32 v66, v66, v67, vcc
	v_mul_f32_e32 v63, v63, v66
	v_add_u32_e32 v66, 0x4200, v70
	ds_write2_b32 v66, v62, v63 offset1:132
	v_fmamk_f32 v62, v68, 0x3c000000, v169
	v_cmp_gt_f32_e32 vcc, s57, v62
	v_mul_f32_e32 v63, 0x4b800000, v62
	s_nop 0
	v_cndmask_b32_e32 v62, v62, v63, vcc
	v_rsq_f32_e32 v62, v62
	s_nop 0
	v_mul_f32_e32 v63, 0x45800000, v62
	v_cndmask_b32_e32 v62, v62, v63, vcc
	v_fmamk_f32 v63, v69, 0x3c000000, v169
	v_mul_f32_e32 v62, v64, v62
	v_cmp_gt_f32_e32 vcc, s57, v63
	v_mul_f32_e32 v64, 0x4b800000, v63
	s_nop 0
	v_cndmask_b32_e32 v63, v63, v64, vcc
	v_rsq_f32_e32 v63, v63
	s_nop 0
	v_mul_f32_e32 v64, 0x45800000, v63
	v_cndmask_b32_e32 v63, v63, v64, vcc
	v_mul_f32_e32 v63, v65, v63
	v_add_u32_e32 v64, 0x4600, v70
	ds_write2_b32 v64, v62, v63 offset0:8 offset1:140
	s_waitcnt lgkmcnt(8)
	v_pk_add_f32 v[68:69], v[214:215], v[218:219]
	s_waitcnt lgkmcnt(8)
	v_pk_add_f32 v[66:67], v[212:213], v[216:217]
	s_waitcnt lgkmcnt(7)
	v_pk_add_f32 v[68:69], v[68:69], v[222:223]
	s_waitcnt lgkmcnt(7)
	v_pk_add_f32 v[66:67], v[66:67], v[220:221]
	s_waitcnt lgkmcnt(6)
	v_pk_add_f32 v[68:69], v[68:69], v[226:227]
	s_waitcnt lgkmcnt(6)
	v_pk_add_f32 v[66:67], v[66:67], v[224:225]
	s_waitcnt lgkmcnt(5)
	v_pk_add_f32 v[68:69], v[68:69], v[230:231]
	s_waitcnt lgkmcnt(5)
	v_pk_add_f32 v[66:67], v[66:67], v[228:229]
	s_waitcnt lgkmcnt(4)
	v_pk_add_f32 v[68:69], v[68:69], v[234:235]
	s_waitcnt lgkmcnt(4)
	v_pk_add_f32 v[66:67], v[66:67], v[232:233]
	s_waitcnt lgkmcnt(3)
	v_pk_add_f32 v[68:69], v[68:69], v[238:239]
	s_waitcnt lgkmcnt(3)
	v_pk_add_f32 v[66:67], v[66:67], v[236:237]
	s_waitcnt lgkmcnt(2)
	v_pk_add_f32 v[62:63], v[66:67], v[240:241]
	s_nop 0
	v_fmamk_f32 v62, v62, 0x3c000000, v169
	v_cmp_gt_f32_e32 vcc, s57, v62
	v_mul_f32_e32 v66, 0x4b800000, v62
	s_waitcnt lgkmcnt(2)
	v_pk_add_f32 v[64:65], v[68:69], v[242:243]
	v_cndmask_b32_e32 v62, v62, v66, vcc
	v_rsq_f32_e32 v62, v62
	s_cmp_lt_u32 s22, 30
	s_cbranch_scc0 .Lrv_c2_n0
	s_waitcnt vmcnt(4)
	s_branch .Lrv_c2_end

.Lrv_c2_end:
	v_and_b32_e32 v67, 0xffff0000, v46
	v_mul_f32_e32 v66, 0x45800000, v62
	v_cndmask_b32_e32 v62, v62, v66, vcc
	v_mul_f32_e32 v58, v58, v62
	v_fmamk_f32 v62, v63, 0x3c000000, v169
	v_cmp_gt_f32_e32 vcc, s57, v62
	v_mul_f32_e32 v63, 0x4b800000, v62
	v_lshlrev_b32_e32 v66, 16, v46
	v_cndmask_b32_e32 v62, v62, v63, vcc
	v_rsq_f32_e32 v62, v62
	s_nop 0
	v_mul_f32_e32 v63, 0x45800000, v62
	v_cndmask_b32_e32 v62, v62, v63, vcc
	v_mul_f32_e32 v59, v59, v62
	v_add_u32_e32 v62, 0x6200, v70
	ds_write2_b32 v62, v58, v59 offset0:64 offset1:196
	v_fmamk_f32 v58, v64, 0x3c000000, v169
	v_cmp_gt_f32_e32 vcc, s57, v58
	v_mul_f32_e32 v59, 0x4b800000, v58
	s_nop 0
	v_cndmask_b32_e32 v58, v58, v59, vcc
	v_rsq_f32_e32 v58, v58
	s_nop 0
	v_mul_f32_e32 v59, 0x45800000, v58
	v_cndmask_b32_e32 v58, v58, v59, vcc
	v_fmamk_f32 v59, v65, 0x3c000000, v169
	v_mul_f32_e32 v58, v60, v58
	v_cmp_gt_f32_e32 vcc, s57, v59
	v_mul_f32_e32 v60, 0x4b800000, v59
	s_nop 0
	v_cndmask_b32_e32 v59, v59, v60, vcc
	v_rsq_f32_e32 v59, v59
	s_nop 0
	v_mul_f32_e32 v60, 0x45800000, v59
	v_cndmask_b32_e32 v59, v59, v60, vcc
	v_mul_f32_e32 v59, v61, v59
	v_add_u32_e32 v60, 0x6600, v70
	ds_write2_b32 v60, v58, v59 offset0:72 offset1:204
	ds_read_b128 v[58:61], v113
	ds_read_b128 v[62:65], v113 offset:16
	s_waitcnt lgkmcnt(1)
	v_pk_mul_f32 v[58:59], v[58:59], v[66:67]
	s_nop 0
	v_cvt_pk_bf16_f32 v46, v58, v59
	v_lshlrev_b32_e32 v58, 16, v47
	v_and_b32_e32 v59, 0xffff0000, v47
	v_pk_mul_f32 v[58:59], v[60:61], v[58:59]
	s_nop 0
	v_cvt_pk_bf16_f32 v47, v58, v59
	v_lshlrev_b32_e32 v58, 16, v48
	v_and_b32_e32 v59, 0xffff0000, v48
	s_waitcnt lgkmcnt(0)
	v_pk_mul_f32 v[58:59], v[62:63], v[58:59]
	s_nop 0
	v_cvt_pk_bf16_f32 v48, v58, v59
	v_lshlrev_b32_e32 v58, 16, v49
	v_and_b32_e32 v59, 0xffff0000, v49
	v_pk_mul_f32 v[58:59], v[64:65], v[58:59]
	s_nop 0
	v_cvt_pk_bf16_f32 v49, v58, v59
	v_add_co_u32_e32 v58, vcc, s4, v96
	s_nop 1
	v_addc_co_u32_e32 v59, vcc, 0, v97, vcc
	s_andn2_b64 vcc, exec, s[48:49]
	global_store_dwordx4 v[58:59], v[46:49], off
	s_cbranch_vccz .LBB0_271

.LBB0_199:
	s_or_b64 exec, exec, s[48:49]
	s_mul_i32 s4, s22, 0xab
	s_bfe_u32 s4, s4, 0x70009
	s_mul_i32 s4, s4, 3
	s_sub_i32 s4, s22, s4
	v_cvt_pk_bf16_f32 v58, v58, v59
	v_cvt_pk_bf16_f32 v59, v60, v61
	s_and_b32 s4, s4, 0xff
	ds_write_b64 v116, v[58:59]
	v_ashrrev_i32_e32 v58, 2, v97
	v_lshlrev_b32_e32 v83, 2, v96
	s_mul_i32 s4, s4, 0x8c00
	v_add_u32_e32 v119, v58, v83
	v_lshlrev_b32_e32 v58, 3, v97
	v_add_u32_e32 v62, s4, v168
	v_and_b32_e32 v58, 24, v58
	v_mul_lo_u32 v59, v119, s65
	v_add_u32_e32 v132, v62, v58
	v_add3_u32 v58, v132, v118, v59
	v_lshl_add_u32 v134, v96, 3, v62
	v_add_u32_e32 v62, v144, v108
	ds_read_b64_tr_b16 v[136:137], v58 offset:18432
	ds_read_b64_tr_b16 v[138:139], v58 offset:22784
	ds_read_b64_tr_b16 v[152:153], v58 offset:27136
	ds_read_b64_tr_b16 v[154:155], v58 offset:31488
	ds_read_b128 v[156:159], v62
	v_add_u32_e32 v140, s45, v97
	v_mad_u64_u32 v[160:161], s[4:5], v140, s56, v[134:135]
	ds_read2_b64 v[170:173], v160 offset1:4
	ds_read2_b64 v[174:177], v160 offset0:8 offset1:12
	v_add_u32_e32 v141, v144, v114
	ds_read_b128 v[178:181], v141 offset:1024
	ds_read_b128 v[182:185], v141
	v_add_u32_e32 v142, s43, v97
	v_mad_u64_u32 v[162:163], s[4:5], v142, s56, v[134:135]
	ds_read2_b64 v[186:189], v162 offset1:4
	ds_read2_b64 v[190:193], v162 offset0:8 offset1:12
	v_mad_u64_u32 v[194:195], s[4:5], v119, s56, v[132:133]
	ds_read_b64_tr_b16 v[196:197], v194 offset:9216
	ds_read_b64_tr_b16 v[200:201], v194 offset:9248
	ds_read_b64_tr_b16 v[198:199], v194 offset:11520
	ds_read_b64_tr_b16 v[212:213], v194 offset:13824
	ds_read_b64_tr_b16 v[214:215], v194 offset:16128
	ds_read_b64_tr_b16 v[202:203], v194 offset:11552
	ds_read_b64_tr_b16 v[216:217], v194 offset:13856
	ds_read_b64_tr_b16 v[218:219], v194 offset:16160
	ds_read_b64_tr_b16 v[220:221], v194 offset:9280
	ds_read_b64_tr_b16 v[222:223], v194 offset:11584
	ds_read_b64_tr_b16 v[224:225], v194 offset:13888
	ds_read_b64_tr_b16 v[226:227], v194 offset:16192
	ds_read_b64_tr_b16 v[228:229], v194 offset:9312
	ds_read_b64_tr_b16 v[230:231], v194 offset:11616
	ds_read_b64_tr_b16 v[232:233], v194 offset:13920
	ds_read_b64_tr_b16 v[234:235], v194 offset:16224
	s_waitcnt lgkmcnt(15)
	v_mfma_f32_16x16x32_bf16 v[62:65], v[156:159], v[136:139], v[0:3]
	v_cvt_pk_bf16_f32 v58, v50, v51
	v_cvt_pk_bf16_f32 v59, v52, v53
	v_cvt_pk_bf16_f32 v60, v38, v39
	v_cvt_pk_bf16_f32 v61, v40, v41
	v_cvt_pk_bf16_f32 v120, v42, v43
	v_cvt_pk_bf16_f32 v121, v44, v45
	s_waitcnt lgkmcnt(15)
	v_mfma_f32_16x16x32_bf16 v[62:65], v[170:173], v[58:61], v[62:65]
	v_cvt_pk_bf16_f32 v122, v54, v55
	v_cvt_pk_bf16_f32 v123, v56, v57
	s_waitcnt lgkmcnt(15)
	s_nop 1
	v_mfma_f32_16x16x32_bf16 v[62:65], v[174:177], v[120:123], v[62:65]
	s_waitcnt lgkmcnt(15)
	v_mfma_f32_16x16x32_bf16 v[124:127], v[182:185], v[136:139], v[0:3]
	v_mov_b32_e32 v81, v80
	v_pk_mul_f32 v[52:53], v[80:81], v[52:53]
	v_pk_mul_f32 v[50:51], v[84:85], v[50:51]
	s_waitcnt lgkmcnt(15)
	v_mfma_f32_16x16x32_bf16 v[124:127], v[178:181], v[152:155], v[124:127]
	v_pk_mul_f32 v[40:41], v[80:81], v[40:41]
	v_pk_mul_f32 v[38:39], v[84:85], v[38:39]
	s_waitcnt lgkmcnt(15)
	v_mfma_f32_16x16x32_bf16 v[58:61], v[186:189], v[58:61], v[124:127]
	s_nop 2
	s_waitcnt lgkmcnt(15)
	v_mfma_f32_16x16x32_bf16 v[58:61], v[190:193], v[120:123], v[58:61]
	v_pk_mul_f32 v[44:45], v[80:81], v[44:45]
	v_pk_mul_f32 v[42:43], v[84:85], v[42:43]
	s_waitcnt lgkmcnt(13)
	v_mfma_f32_16x16x32_bf16 v[50:53], v[196:199], v[136:139], v[50:53]
	v_pk_mul_f32 v[56:57], v[80:81], v[56:57]
	s_waitcnt lgkmcnt(11)
	v_mfma_f32_16x16x32_bf16 v[50:53], v[212:215], v[152:155], v[50:53]
	v_pk_mul_f32 v[54:55], v[84:85], v[54:55]
	v_cmp_eq_u32_e32 vcc, 0, v97
	s_waitcnt lgkmcnt(10)
	v_mfma_f32_16x16x32_bf16 v[38:41], v[200:203], v[136:139], v[38:41]
	s_waitcnt lgkmcnt(8)
	v_mfma_f32_16x16x32_bf16 v[38:41], v[216:219], v[152:155], v[38:41]
	s_waitcnt lgkmcnt(6)
	v_mfma_f32_16x16x32_bf16 v[42:45], v[220:223], v[136:139], v[42:45]
	s_waitcnt lgkmcnt(4)
	v_mfma_f32_16x16x32_bf16 v[42:45], v[224:227], v[152:155], v[42:45]
	s_waitcnt lgkmcnt(2)
	v_mfma_f32_16x16x32_bf16 v[54:57], v[228:231], v[136:139], v[54:57]
	s_waitcnt lgkmcnt(0)
	v_mfma_f32_16x16x32_bf16 v[54:57], v[232:235], v[152:155], v[54:57]
	v_mul_f32_e32 v67, v62, v62
	v_mov_b32_e32 v68, v165
	v_add_u32_e32 v66, v83, v112
	v_lshl_add_u32 v66, v66, 2, v143
	v_mov_b32_dpp v68, v67 quad_perm:[1,0,3,2] row_mask:0xf bank_mask:0xf
	v_fmac_f32_e32 v68, v62, v62
	s_nop 1
	v_add_f32_dpp v67, v68, v68 quad_perm:[2,3,0,1] row_mask:0xf bank_mask:0xf bound_ctrl:1
	v_mov_b32_e32 v68, 0
	s_nop 0
	v_add_f32_dpp v67, v67, v67 row_half_mirror row_mask:0xf bank_mask:0xf bound_ctrl:1
	s_nop 1
	v_mov_b32_dpp v68, v67 row_mirror row_mask:0xf bank_mask:0xf
	s_and_saveexec_b64 s[4:5], vcc
	v_add_f32_e32 v67, v67, v68
	ds_write_b32 v66, v67
	s_or_b64 exec, exec, s[4:5]
	v_mul_f32_e32 v67, v63, v63
	v_mov_b32_e32 v68, v165
	s_nop 1
	v_mov_b32_dpp v68, v67 quad_perm:[1,0,3,2] row_mask:0xf bank_mask:0xf
	v_fmac_f32_e32 v68, v63, v63
	s_nop 1
	v_add_f32_dpp v67, v68, v68 quad_perm:[2,3,0,1] row_mask:0xf bank_mask:0xf bound_ctrl:1
	v_mov_b32_e32 v68, 0
	s_nop 0
	v_add_f32_dpp v67, v67, v67 row_half_mirror row_mask:0xf bank_mask:0xf bound_ctrl:1
	s_nop 1
	v_mov_b32_dpp v68, v67 row_mirror row_mask:0xf bank_mask:0xf
	s_and_saveexec_b64 s[4:5], vcc
	v_add_f32_e32 v67, v67, v68
	ds_write_b32 v66, v67 offset:4
	s_or_b64 exec, exec, s[4:5]
	v_mul_f32_e32 v67, v64, v64
	v_mov_b32_e32 v68, v165
	s_nop 1
	v_mov_b32_dpp v68, v67 quad_perm:[1,0,3,2] row_mask:0xf bank_mask:0xf
	v_fmac_f32_e32 v68, v64, v64
	s_nop 1
	v_add_f32_dpp v67, v68, v68 quad_perm:[2,3,0,1] row_mask:0xf bank_mask:0xf bound_ctrl:1
	v_mov_b32_e32 v68, 0
	s_nop 0
	v_add_f32_dpp v67, v67, v67 row_half_mirror row_mask:0xf bank_mask:0xf bound_ctrl:1
	s_nop 1
	v_mov_b32_dpp v68, v67 row_mirror row_mask:0xf bank_mask:0xf
	s_and_saveexec_b64 s[4:5], vcc
	v_add_f32_e32 v67, v67, v68
	ds_write_b32 v66, v67 offset:8
	s_or_b64 exec, exec, s[4:5]
	v_mul_f32_e32 v67, v65, v65
	v_mov_b32_e32 v68, v165
	s_nop 1
	v_mov_b32_dpp v68, v67 quad_perm:[1,0,3,2] row_mask:0xf bank_mask:0xf
	v_fmac_f32_e32 v68, v65, v65
	s_nop 1
	v_add_f32_dpp v67, v68, v68 quad_perm:[2,3,0,1] row_mask:0xf bank_mask:0xf bound_ctrl:1
	v_mov_b32_e32 v68, 0
	s_nop 0
	v_add_f32_dpp v67, v67, v67 row_half_mirror row_mask:0xf bank_mask:0xf bound_ctrl:1
	s_nop 1
	v_mov_b32_dpp v68, v67 row_mirror row_mask:0xf bank_mask:0xf
	s_and_saveexec_b64 s[4:5], vcc
	v_add_f32_e32 v67, v67, v68
	ds_write_b32 v66, v67 offset:12
	s_or_b64 exec, exec, s[4:5]
	v_mul_f32_e32 v67, v58, v58
	v_mov_b32_e32 v68, v165
	s_nop 1
	v_mov_b32_dpp v68, v67 quad_perm:[1,0,3,2] row_mask:0xf bank_mask:0xf
	v_fmac_f32_e32 v68, v58, v58
	s_nop 1
	v_add_f32_dpp v67, v68, v68 quad_perm:[2,3,0,1] row_mask:0xf bank_mask:0xf bound_ctrl:1
	v_mov_b32_e32 v68, 0
	s_nop 0
	v_add_f32_dpp v67, v67, v67 row_half_mirror row_mask:0xf bank_mask:0xf bound_ctrl:1
	s_nop 1
	v_mov_b32_dpp v68, v67 row_mirror row_mask:0xf bank_mask:0xf
	s_and_saveexec_b64 s[4:5], vcc
	v_add_f32_e32 v67, v67, v68
	ds_write_b32 v66, v67 offset:64
	s_or_b64 exec, exec, s[4:5]
	v_mul_f32_e32 v67, v59, v59
	v_mov_b32_e32 v68, v165
	s_nop 1
	v_mov_b32_dpp v68, v67 quad_perm:[1,0,3,2] row_mask:0xf bank_mask:0xf
	v_fmac_f32_e32 v68, v59, v59
	s_nop 1
	v_add_f32_dpp v67, v68, v68 quad_perm:[2,3,0,1] row_mask:0xf bank_mask:0xf bound_ctrl:1
	v_mov_b32_e32 v68, 0
	s_nop 0
	v_add_f32_dpp v67, v67, v67 row_half_mirror row_mask:0xf bank_mask:0xf bound_ctrl:1
	s_nop 1
	v_mov_b32_dpp v68, v67 row_mirror row_mask:0xf bank_mask:0xf
	s_and_saveexec_b64 s[4:5], vcc
	v_add_f32_e32 v67, v67, v68
	ds_write_b32 v66, v67 offset:68
	s_or_b64 exec, exec, s[4:5]
	v_mul_f32_e32 v67, v60, v60
	v_mov_b32_e32 v68, v165
	s_nop 1
	v_mov_b32_dpp v68, v67 quad_perm:[1,0,3,2] row_mask:0xf bank_mask:0xf
	v_fmac_f32_e32 v68, v60, v60
	s_nop 1
	v_add_f32_dpp v67, v68, v68 quad_perm:[2,3,0,1] row_mask:0xf bank_mask:0xf bound_ctrl:1
	v_mov_b32_e32 v68, 0
	s_nop 0
	v_add_f32_dpp v67, v67, v67 row_half_mirror row_mask:0xf bank_mask:0xf bound_ctrl:1
	s_nop 1
	v_mov_b32_dpp v68, v67 row_mirror row_mask:0xf bank_mask:0xf
	s_and_saveexec_b64 s[4:5], vcc
	v_add_f32_e32 v67, v67, v68
	ds_write_b32 v66, v67 offset:72
	s_or_b64 exec, exec, s[4:5]
	v_mul_f32_e32 v67, v61, v61
	v_mov_b32_e32 v68, v165
	s_nop 1
	v_mov_b32_dpp v68, v67 quad_perm:[1,0,3,2] row_mask:0xf bank_mask:0xf
	v_fmac_f32_e32 v68, v61, v61
	s_nop 1
	v_add_f32_dpp v67, v68, v68 quad_perm:[2,3,0,1] row_mask:0xf bank_mask:0xf bound_ctrl:1
	v_mov_b32_e32 v68, 0
	s_nop 0
	v_add_f32_dpp v67, v67, v67 row_half_mirror row_mask:0xf bank_mask:0xf bound_ctrl:1
	s_nop 1
	v_mov_b32_dpp v68, v67 row_mirror row_mask:0xf bank_mask:0xf
	s_and_saveexec_b64 s[4:5], vcc
	v_add_f32_e32 v67, v67, v68
	ds_write_b32 v66, v67 offset:76
	s_or_b64 exec, exec, s[4:5]
	s_add_i32 s23, s22, 2
	s_cmp_lt_u32 s22, 30
	s_cselect_b64 s[50:51], -1, 0
	s_cmp_gt_u32 s22, 29
	s_cselect_b64 s[48:49], -1, 0
	s_and_b64 vcc, exec, s[48:49]
	v_lshlrev_b32_e32 v119, 1, v164
	s_cbranch_vccnz .LBB0_217
	s_mul_i32 s4, s23, 0xab
	s_bfe_u32 s4, s4, 0x70009
	s_mul_i32 s4, s4, 3
	s_sub_i32 s4, s23, s4
	s_and_b32 s4, s4, 0xff
	s_mul_i32 s4, s4, 0x8c00
	v_add_u32_e32 v66, s4, v76
	v_lshl_add_u32 v67, v106, 1, v66
	v_add3_u32 v66, v66, v77, v119
	s_cmp_eq_u32 s22, 0
	s_cbranch_scc0 .Lrv_b1_n0
	s_waitcnt vmcnt(4)
	s_branch .Lrv_b1_end
.Lrv_b1_n0:
	s_waitcnt vmcnt(6)
.Lrv_b1_end:
	ds_write_b128 v67, v[22:25]
	ds_write_b128 v67, v[26:29] offset:9216
	ds_write_b128 v66, v[30:33] offset:18432
	ds_write_b128 v66, v[34:37] offset:18448
.LBB0_217:
	v_lshl_add_u32 v81, v83, 2, v143
	s_waitcnt lgkmcnt(0)
	s_barrier
	ds_read_b128 v[170:173], v81
	ds_read_b128 v[174:177], v81 offset:256
	ds_read_b128 v[178:181], v81 offset:512
	ds_read_b128 v[182:185], v81 offset:768
	ds_read_b128 v[186:189], v81 offset:1024
	ds_read_b128 v[190:193], v81 offset:1280
	ds_read_b128 v[194:197], v81 offset:1536
	ds_read_b128 v[198:201], v81 offset:1792
	ds_read_b128 v[212:215], v81 offset:64
	ds_read_b128 v[216:219], v81 offset:320
	ds_read_b128 v[220:223], v81 offset:576
	ds_read_b128 v[224:227], v81 offset:832
	ds_read_b128 v[228:231], v81 offset:1088
	ds_read_b128 v[232:235], v81 offset:1344
	ds_read_b128 v[236:239], v81 offset:1600
	ds_read_b128 v[240:243], v81 offset:1856
	s_waitcnt lgkmcnt(14)
	v_pk_add_f32 v[72:73], v[172:173], v[176:177]
	s_waitcnt lgkmcnt(14)
	v_pk_add_f32 v[70:71], v[170:171], v[174:175]
	s_waitcnt lgkmcnt(13)
	v_pk_add_f32 v[72:73], v[72:73], v[180:181]
	s_waitcnt lgkmcnt(13)
	v_pk_add_f32 v[70:71], v[70:71], v[178:179]
	s_waitcnt lgkmcnt(12)
	v_pk_add_f32 v[72:73], v[72:73], v[184:185]
	s_waitcnt lgkmcnt(12)
	v_pk_add_f32 v[70:71], v[70:71], v[182:183]
	s_waitcnt lgkmcnt(11)
	v_pk_add_f32 v[72:73], v[72:73], v[188:189]
	s_waitcnt lgkmcnt(11)
	v_pk_add_f32 v[70:71], v[70:71], v[186:187]
	s_waitcnt lgkmcnt(10)
	v_pk_add_f32 v[72:73], v[72:73], v[192:193]
	s_waitcnt lgkmcnt(10)
	v_pk_add_f32 v[70:71], v[70:71], v[190:191]
	s_waitcnt lgkmcnt(9)
	v_pk_add_f32 v[72:73], v[72:73], v[196:197]
	s_waitcnt lgkmcnt(9)
	v_pk_add_f32 v[70:71], v[70:71], v[194:195]
	s_waitcnt lgkmcnt(8)
	v_pk_add_f32 v[66:67], v[70:71], v[198:199]
	s_nop 0
	v_fmamk_f32 v66, v66, 0x3c000000, v169
	v_cmp_gt_f32_e32 vcc, s57, v66
	v_mul_f32_e32 v70, 0x4b800000, v66
	s_waitcnt lgkmcnt(8)
	v_pk_add_f32 v[68:69], v[72:73], v[200:201]
	v_cndmask_b32_e32 v66, v66, v70, vcc
	v_rsq_f32_e32 v66, v66
	s_nop 0
	v_mul_f32_e32 v70, 0x45800000, v66
	v_cndmask_b32_e32 v66, v66, v70, vcc
	v_mul_f32_e32 v62, v62, v66
	v_lshlrev_b32_e32 v66, 2, v97
	v_mul_lo_u32 v70, v96, s62
	v_add3_u32 v70, v115, v66, v70
	v_fmamk_f32 v66, v67, 0x3c000000, v169
	v_cmp_gt_f32_e32 vcc, s57, v66
	v_mul_f32_e32 v67, 0x4b800000, v66
	v_lshl_add_u64 v[96:97], s[96:97], 0, v[92:93]
	v_cndmask_b32_e32 v66, v66, v67, vcc
	v_rsq_f32_e32 v66, v66
	s_nop 0
	v_mul_f32_e32 v67, 0x45800000, v66
	v_cndmask_b32_e32 v66, v66, v67, vcc
	v_mul_f32_e32 v63, v63, v66
	ds_write2_b32 v70, v62, v63 offset1:132
	v_fmamk_f32 v62, v68, 0x3c000000, v169
	v_cmp_gt_f32_e32 vcc, s57, v62
	v_mul_f32_e32 v63, 0x4b800000, v62
	s_nop 0
	v_cndmask_b32_e32 v62, v62, v63, vcc
	v_rsq_f32_e32 v62, v62
	s_nop 0
	v_mul_f32_e32 v63, 0x45800000, v62
	v_cndmask_b32_e32 v62, v62, v63, vcc
	v_fmamk_f32 v63, v69, 0x3c000000, v169
	v_mul_f32_e32 v62, v64, v62
	v_cmp_gt_f32_e32 vcc, s57, v63
	v_mul_f32_e32 v64, 0x4b800000, v63
	s_nop 0
	v_cndmask_b32_e32 v63, v63, v64, vcc
	v_rsq_f32_e32 v63, v63
	s_nop 0
	v_mul_f32_e32 v64, 0x45800000, v63
	v_cndmask_b32_e32 v63, v63, v64, vcc
	v_mul_f32_e32 v63, v65, v63
	v_add_u32_e32 v64, 0x400, v70
	ds_write2_b32 v64, v62, v63 offset0:8 offset1:140
	s_waitcnt lgkmcnt(8)
	v_pk_add_f32 v[68:69], v[214:215], v[218:219]
	s_waitcnt lgkmcnt(8)
	v_pk_add_f32 v[66:67], v[212:213], v[216:217]
	s_waitcnt lgkmcnt(7)
	v_pk_add_f32 v[68:69], v[68:69], v[222:223]
	s_waitcnt lgkmcnt(7)
	v_pk_add_f32 v[66:67], v[66:67], v[220:221]
	s_waitcnt lgkmcnt(6)
	v_pk_add_f32 v[68:69], v[68:69], v[226:227]
	s_waitcnt lgkmcnt(6)
	v_pk_add_f32 v[66:67], v[66:67], v[224:225]
	s_waitcnt lgkmcnt(5)
	v_pk_add_f32 v[68:69], v[68:69], v[230:231]
	s_waitcnt lgkmcnt(5)
	v_pk_add_f32 v[66:67], v[66:67], v[228:229]
	s_waitcnt lgkmcnt(4)
	v_pk_add_f32 v[68:69], v[68:69], v[234:235]
	s_waitcnt lgkmcnt(4)
	v_pk_add_f32 v[66:67], v[66:67], v[232:233]
	s_waitcnt lgkmcnt(3)
	v_pk_add_f32 v[68:69], v[68:69], v[238:239]
	s_waitcnt lgkmcnt(3)
	v_pk_add_f32 v[66:67], v[66:67], v[236:237]
	s_waitcnt lgkmcnt(2)
	v_pk_add_f32 v[62:63], v[66:67], v[240:241]
	s_nop 0
	v_fmamk_f32 v62, v62, 0x3c000000, v169
	v_cmp_gt_f32_e32 vcc, s57, v62
	v_mul_f32_e32 v66, 0x4b800000, v62
	s_waitcnt lgkmcnt(2)
	v_pk_add_f32 v[64:65], v[68:69], v[242:243]
	v_cndmask_b32_e32 v62, v62, v66, vcc
	v_rsq_f32_e32 v62, v62
	s_nop 0
	v_mul_f32_e32 v66, 0x45800000, v62
	v_cndmask_b32_e32 v62, v62, v66, vcc
	v_mul_f32_e32 v58, v58, v62
	v_fmamk_f32 v62, v63, 0x3c000000, v169
	v_cmp_gt_f32_e32 vcc, s57, v62
	v_mul_f32_e32 v63, 0x4b800000, v62
	s_nop 0
	v_cndmask_b32_e32 v62, v62, v63, vcc
	v_rsq_f32_e32 v62, v62
	s_nop 0
	v_mul_f32_e32 v63, 0x45800000, v62
	v_cndmask_b32_e32 v62, v62, v63, vcc
	v_mul_f32_e32 v59, v59, v62
	v_add_u32_e32 v62, 0x2000, v70
	ds_write2_b32 v62, v58, v59 offset0:64 offset1:196
	v_fmamk_f32 v58, v64, 0x3c000000, v169
	v_cmp_gt_f32_e32 vcc, s57, v58
	v_mul_f32_e32 v59, 0x4b800000, v58
	s_nop 0
	v_cndmask_b32_e32 v58, v58, v59, vcc
	v_rsq_f32_e32 v58, v58
	s_nop 0
	v_mul_f32_e32 v59, 0x45800000, v58
	v_cndmask_b32_e32 v58, v58, v59, vcc
	v_fmamk_f32 v59, v65, 0x3c000000, v169
	v_mul_f32_e32 v58, v60, v58
	v_cmp_gt_f32_e32 vcc, s57, v59
	v_mul_f32_e32 v60, 0x4b800000, v59
	s_nop 0
	v_cndmask_b32_e32 v59, v59, v60, vcc
	v_rsq_f32_e32 v59, v59
	s_nop 0
	v_mul_f32_e32 v60, 0x45800000, v59
	v_cndmask_b32_e32 v59, v59, v60, vcc
	v_mul_f32_e32 v59, v61, v59
	v_add_u32_e32 v60, 0x2400, v70
	s_andn2_b64 vcc, exec, s[52:53]
	ds_write2_b32 v60, v58, v59 offset0:72 offset1:204
	s_cbranch_vccnz .LBB0_219
	ds_read_b128 v[58:61], v109
	ds_read_b128 v[62:65], v109 offset:16
	s_cmp_lt_u32 s22, 29
	s_cbranch_scc0 .Lrv_c1_n0
	s_waitcnt vmcnt(4)
	s_branch .Lrv_c1_end

.Lrv_c1_end:
	v_lshlrev_b32_e32 v66, 16, v46
	v_and_b32_e32 v67, 0xffff0000, v46
	s_waitcnt lgkmcnt(1)
	v_pk_mul_f32 v[58:59], v[58:59], v[66:67]
	s_nop 0
	v_cvt_pk_bf16_f32 v46, v58, v59
	v_lshlrev_b32_e32 v58, 16, v47
	v_and_b32_e32 v59, 0xffff0000, v47
	v_pk_mul_f32 v[58:59], v[60:61], v[58:59]
	s_nop 0
	v_cvt_pk_bf16_f32 v47, v58, v59
	v_lshlrev_b32_e32 v58, 16, v48
	v_and_b32_e32 v59, 0xffff0000, v48
	s_waitcnt lgkmcnt(0)
	v_pk_mul_f32 v[58:59], v[62:63], v[58:59]
	s_nop 0
	v_cvt_pk_bf16_f32 v48, v58, v59
	v_lshlrev_b32_e32 v58, 16, v49
	v_and_b32_e32 v59, 0xffff0000, v49
	v_pk_mul_f32 v[58:59], v[64:65], v[58:59]
	s_nop 0
	v_cvt_pk_bf16_f32 v49, v58, v59
	v_add_co_u32_e32 v58, vcc, 0xa170000, v96
	s_nop 1
	v_addc_co_u32_e32 v59, vcc, 0, v97, vcc
	global_store_dwordx4 v[58:59], v[46:49], off
.LBB0_219:
	s_nop 1
	s_nop 0
	v_add_co_u32_e32 v46, vcc, 0xc180000, v94
	v_mov_b32_e32 v120, v75
	v_mov_b32_e32 v121, v5
	v_addc_co_u32_e32 v47, vcc, 0, v95, vcc
	global_load_dwordx4 v[46:49], v[46:47], off offset:2048
	s_cmp_gt_u32 s22, 27
	s_cbranch_scc1 .LBB0_221
	v_add_co_u32_e32 v26, vcc, 0xc240000, v100
	s_mov_b64 s[4:5], 0xc240400
	s_nop 0
	v_addc_co_u32_e32 v27, vcc, 0, v101, vcc
	v_add_co_u32_e32 v30, vcc, 0xc240000, v98
	v_lshl_add_u64 v[34:35], v[98:99], 0, s[4:5]
	s_nop 0
	v_addc_co_u32_e32 v31, vcc, 0, v99, vcc
	global_load_dwordx4 v[22:25], v[26:27], off
	s_nop 0
	global_load_dwordx4 v[26:29], v[26:27], off offset:512
	s_nop 0
	global_load_dwordx4 v[30:33], v[30:31], off offset:1024
	s_nop 0
	global_load_dwordx4 v[34:37], v[34:35], off offset:16

.LBB0_227:
	s_bfe_u32 s4, s37, 0x70009
	s_mul_i32 s4, s4, 3
	s_sub_i32 s4, s36, s4
	s_and_b32 s4, s4, 0xff
	v_ashrrev_i32_e32 v58, 2, v121
	v_lshlrev_b32_e32 v83, 2, v120
	s_mul_i32 s4, s4, 0x8c00
	v_add_u32_e32 v95, v58, v83
	v_lshlrev_b32_e32 v58, 3, v121
	v_add_u32_e32 v62, s4, v168
	v_and_b32_e32 v58, 24, v58
	v_mul_lo_u32 v59, v95, s65
	v_add_u32_e32 v94, v62, v58
	v_add3_u32 v58, v94, v118, v59
	v_lshl_add_u32 v130, v120, 3, v62
	v_add_u32_e32 v62, v145, v108
	ds_read_b64_tr_b16 v[136:137], v58 offset:18432
	ds_read_b64_tr_b16 v[138:139], v58 offset:22784
	ds_read_b64_tr_b16 v[152:153], v58 offset:27136
	ds_read_b64_tr_b16 v[154:155], v58 offset:31488
	ds_read_b128 v[156:159], v62
	v_add_u32_e32 v140, s45, v121
	v_mad_u64_u32 v[160:161], s[4:5], v140, s56, v[130:131]
	ds_read2_b64 v[170:173], v160 offset1:4
	ds_read2_b64 v[174:177], v160 offset0:8 offset1:12
	v_add_u32_e32 v141, v145, v114
	ds_read_b128 v[178:181], v141 offset:1024
	ds_read_b128 v[182:185], v141
	v_add_u32_e32 v142, s43, v121
	v_mad_u64_u32 v[162:163], s[4:5], v142, s56, v[130:131]
	v_mad_u64_u32 v[186:187], s[4:5], v95, s56, v[94:95]
	ds_read2_b64 v[188:191], v162 offset1:4
	ds_read2_b64 v[192:195], v162 offset0:8 offset1:12
	ds_read_b64_tr_b16 v[196:197], v186 offset:9216
	ds_read_b64_tr_b16 v[200:201], v186 offset:9248
	ds_read_b64_tr_b16 v[198:199], v186 offset:11520
	ds_read_b64_tr_b16 v[212:213], v186 offset:13824
	ds_read_b64_tr_b16 v[214:215], v186 offset:16128
	ds_read_b64_tr_b16 v[202:203], v186 offset:11552
	ds_read_b64_tr_b16 v[216:217], v186 offset:13856
	ds_read_b64_tr_b16 v[218:219], v186 offset:16160
	ds_read_b64_tr_b16 v[220:221], v186 offset:9280
	ds_read_b64_tr_b16 v[222:223], v186 offset:11584
	ds_read_b64_tr_b16 v[224:225], v186 offset:13888
	ds_read_b64_tr_b16 v[226:227], v186 offset:16192
	ds_read_b64_tr_b16 v[228:229], v186 offset:9312
	ds_read_b64_tr_b16 v[230:231], v186 offset:11616
	ds_read_b64_tr_b16 v[232:233], v186 offset:13920
	ds_read_b64_tr_b16 v[234:235], v186 offset:16224
	s_waitcnt lgkmcnt(15)
	v_mfma_f32_16x16x32_bf16 v[62:65], v[156:159], v[136:139], v[0:3]
	v_cvt_pk_bf16_f32 v58, v50, v51
	v_cvt_pk_bf16_f32 v59, v52, v53
	v_cvt_pk_bf16_f32 v60, v38, v39
	v_cvt_pk_bf16_f32 v61, v40, v41
	v_cvt_pk_bf16_f32 v98, v42, v43
	v_cvt_pk_bf16_f32 v99, v44, v45
	s_waitcnt lgkmcnt(15)
	v_mfma_f32_16x16x32_bf16 v[62:65], v[170:173], v[58:61], v[62:65]
	v_cvt_pk_bf16_f32 v100, v54, v55
	v_cvt_pk_bf16_f32 v101, v56, v57
	s_waitcnt lgkmcnt(15)
	s_nop 1
	v_mfma_f32_16x16x32_bf16 v[62:65], v[174:177], v[98:101], v[62:65]
	s_waitcnt lgkmcnt(15)
	v_mfma_f32_16x16x32_bf16 v[122:125], v[182:185], v[136:139], v[0:3]
	v_mov_b32_e32 v81, v80
	s_waitcnt lgkmcnt(15)
	v_mfma_f32_16x16x32_bf16 v[122:125], v[178:181], v[152:155], v[122:125]
	v_pk_mul_f32 v[52:53], v[80:81], v[52:53]
	v_pk_mul_f32 v[50:51], v[84:85], v[50:51]
	s_waitcnt lgkmcnt(15)
	v_mfma_f32_16x16x32_bf16 v[58:61], v[188:191], v[58:61], v[122:125]
	s_nop 2
	v_pk_mul_f32 v[40:41], v[80:81], v[40:41]
	v_pk_mul_f32 v[38:39], v[84:85], v[38:39]
	s_waitcnt lgkmcnt(15)
	v_mfma_f32_16x16x32_bf16 v[58:61], v[192:195], v[98:101], v[58:61]
	v_pk_mul_f32 v[44:45], v[80:81], v[44:45]
	v_pk_mul_f32 v[42:43], v[84:85], v[42:43]
	s_waitcnt lgkmcnt(13)
	v_mfma_f32_16x16x32_bf16 v[50:53], v[196:199], v[136:139], v[50:53]
	v_pk_mul_f32 v[56:57], v[80:81], v[56:57]
	s_waitcnt lgkmcnt(11)
	v_mfma_f32_16x16x32_bf16 v[50:53], v[212:215], v[152:155], v[50:53]
	v_pk_mul_f32 v[54:55], v[84:85], v[54:55]
	v_cmp_eq_u32_e32 vcc, 0, v121
	s_waitcnt lgkmcnt(10)
	v_mfma_f32_16x16x32_bf16 v[38:41], v[200:203], v[136:139], v[38:41]
	s_waitcnt lgkmcnt(8)
	v_mfma_f32_16x16x32_bf16 v[38:41], v[216:219], v[152:155], v[38:41]
	s_waitcnt lgkmcnt(6)
	v_mfma_f32_16x16x32_bf16 v[42:45], v[220:223], v[136:139], v[42:45]
	s_waitcnt lgkmcnt(4)
	v_mfma_f32_16x16x32_bf16 v[42:45], v[224:227], v[152:155], v[42:45]
	s_waitcnt lgkmcnt(2)
	v_mfma_f32_16x16x32_bf16 v[54:57], v[228:231], v[136:139], v[54:57]
	s_waitcnt lgkmcnt(0)
	v_mfma_f32_16x16x32_bf16 v[54:57], v[232:235], v[152:155], v[54:57]
	v_mul_f32_e32 v67, v62, v62
	v_mov_b32_e32 v68, v165
	v_add_u32_e32 v66, v83, v112
	v_lshl_add_u32 v66, v66, 2, v147
	v_mov_b32_dpp v68, v67 quad_perm:[1,0,3,2] row_mask:0xf bank_mask:0xf
	v_fmac_f32_e32 v68, v62, v62
	s_nop 1
	v_add_f32_dpp v67, v68, v68 quad_perm:[2,3,0,1] row_mask:0xf bank_mask:0xf bound_ctrl:1
	v_mov_b32_e32 v68, 0
	s_nop 0
	v_add_f32_dpp v67, v67, v67 row_half_mirror row_mask:0xf bank_mask:0xf bound_ctrl:1
	s_nop 1
	v_mov_b32_dpp v68, v67 row_mirror row_mask:0xf bank_mask:0xf
	s_and_saveexec_b64 s[4:5], vcc
	v_add_f32_e32 v67, v67, v68
	ds_write_b32 v66, v67
	s_or_b64 exec, exec, s[4:5]
	v_mul_f32_e32 v67, v63, v63
	v_mov_b32_e32 v68, v165
	s_nop 1
	v_mov_b32_dpp v68, v67 quad_perm:[1,0,3,2] row_mask:0xf bank_mask:0xf
	v_fmac_f32_e32 v68, v63, v63
	s_nop 1
	v_add_f32_dpp v67, v68, v68 quad_perm:[2,3,0,1] row_mask:0xf bank_mask:0xf bound_ctrl:1
	v_mov_b32_e32 v68, 0
	s_nop 0
	v_add_f32_dpp v67, v67, v67 row_half_mirror row_mask:0xf bank_mask:0xf bound_ctrl:1
	s_nop 1
	v_mov_b32_dpp v68, v67 row_mirror row_mask:0xf bank_mask:0xf
	s_and_saveexec_b64 s[4:5], vcc
	v_add_f32_e32 v67, v67, v68
	ds_write_b32 v66, v67 offset:4
	s_or_b64 exec, exec, s[4:5]
	v_mul_f32_e32 v67, v64, v64
	v_mov_b32_e32 v68, v165
	s_nop 1
	v_mov_b32_dpp v68, v67 quad_perm:[1,0,3,2] row_mask:0xf bank_mask:0xf
	v_fmac_f32_e32 v68, v64, v64
	s_nop 1
	v_add_f32_dpp v67, v68, v68 quad_perm:[2,3,0,1] row_mask:0xf bank_mask:0xf bound_ctrl:1
	v_mov_b32_e32 v68, 0
	s_nop 0
	v_add_f32_dpp v67, v67, v67 row_half_mirror row_mask:0xf bank_mask:0xf bound_ctrl:1
	s_nop 1
	v_mov_b32_dpp v68, v67 row_mirror row_mask:0xf bank_mask:0xf
	s_and_saveexec_b64 s[4:5], vcc
	v_add_f32_e32 v67, v67, v68
	ds_write_b32 v66, v67 offset:8
	s_or_b64 exec, exec, s[4:5]
	v_mul_f32_e32 v67, v65, v65
	v_mov_b32_e32 v68, v165
	s_nop 1
	v_mov_b32_dpp v68, v67 quad_perm:[1,0,3,2] row_mask:0xf bank_mask:0xf
	v_fmac_f32_e32 v68, v65, v65
	s_nop 1
	v_add_f32_dpp v67, v68, v68 quad_perm:[2,3,0,1] row_mask:0xf bank_mask:0xf bound_ctrl:1
	v_mov_b32_e32 v68, 0
	s_nop 0
	v_add_f32_dpp v67, v67, v67 row_half_mirror row_mask:0xf bank_mask:0xf bound_ctrl:1
	s_nop 1
	v_mov_b32_dpp v68, v67 row_mirror row_mask:0xf bank_mask:0xf
	s_and_saveexec_b64 s[4:5], vcc
	v_add_f32_e32 v67, v67, v68
	ds_write_b32 v66, v67 offset:12
	s_or_b64 exec, exec, s[4:5]
	v_mul_f32_e32 v67, v58, v58
	v_mov_b32_e32 v68, v165
	s_nop 1
	v_mov_b32_dpp v68, v67 quad_perm:[1,0,3,2] row_mask:0xf bank_mask:0xf
	v_fmac_f32_e32 v68, v58, v58
	s_nop 1
	v_add_f32_dpp v67, v68, v68 quad_perm:[2,3,0,1] row_mask:0xf bank_mask:0xf bound_ctrl:1
	v_mov_b32_e32 v68, 0
	s_nop 0
	v_add_f32_dpp v67, v67, v67 row_half_mirror row_mask:0xf bank_mask:0xf bound_ctrl:1
	s_nop 1
	v_mov_b32_dpp v68, v67 row_mirror row_mask:0xf bank_mask:0xf
	s_and_saveexec_b64 s[4:5], vcc
	v_add_f32_e32 v67, v67, v68
	ds_write_b32 v66, v67 offset:64
	s_or_b64 exec, exec, s[4:5]
	v_mul_f32_e32 v67, v59, v59
	v_mov_b32_e32 v68, v165
	s_nop 1
	v_mov_b32_dpp v68, v67 quad_perm:[1,0,3,2] row_mask:0xf bank_mask:0xf
	v_fmac_f32_e32 v68, v59, v59
	s_nop 1
	v_add_f32_dpp v67, v68, v68 quad_perm:[2,3,0,1] row_mask:0xf bank_mask:0xf bound_ctrl:1
	v_mov_b32_e32 v68, 0
	s_nop 0
	v_add_f32_dpp v67, v67, v67 row_half_mirror row_mask:0xf bank_mask:0xf bound_ctrl:1
	s_nop 1
	v_mov_b32_dpp v68, v67 row_mirror row_mask:0xf bank_mask:0xf
	s_and_saveexec_b64 s[4:5], vcc
	v_add_f32_e32 v67, v67, v68
	ds_write_b32 v66, v67 offset:68
	s_or_b64 exec, exec, s[4:5]
	v_mul_f32_e32 v67, v60, v60
	v_mov_b32_e32 v68, v165
	s_nop 1
	v_mov_b32_dpp v68, v67 quad_perm:[1,0,3,2] row_mask:0xf bank_mask:0xf
	v_fmac_f32_e32 v68, v60, v60
	s_nop 1
	v_add_f32_dpp v67, v68, v68 quad_perm:[2,3,0,1] row_mask:0xf bank_mask:0xf bound_ctrl:1
	v_mov_b32_e32 v68, 0
	s_nop 0
	v_add_f32_dpp v67, v67, v67 row_half_mirror row_mask:0xf bank_mask:0xf bound_ctrl:1
	s_nop 1
	v_mov_b32_dpp v68, v67 row_mirror row_mask:0xf bank_mask:0xf
	s_and_saveexec_b64 s[4:5], vcc
	v_add_f32_e32 v67, v67, v68
	ds_write_b32 v66, v67 offset:72
	s_or_b64 exec, exec, s[4:5]
	v_mul_f32_e32 v67, v61, v61
	v_mov_b32_e32 v68, v165
	s_nop 1
	v_mov_b32_dpp v68, v67 quad_perm:[1,0,3,2] row_mask:0xf bank_mask:0xf
	v_fmac_f32_e32 v68, v61, v61
	s_nop 1
	v_add_f32_dpp v67, v68, v68 quad_perm:[2,3,0,1] row_mask:0xf bank_mask:0xf bound_ctrl:1
	v_mov_b32_e32 v68, 0
	s_nop 0
	v_add_f32_dpp v67, v67, v67 row_half_mirror row_mask:0xf bank_mask:0xf bound_ctrl:1
	s_nop 1
	v_mov_b32_dpp v68, v67 row_mirror row_mask:0xf bank_mask:0xf
	s_and_saveexec_b64 s[4:5], vcc
	v_add_f32_e32 v67, v67, v68
	ds_write_b32 v66, v67 offset:76
	s_or_b64 exec, exec, s[4:5]
	s_andn2_b64 vcc, exec, s[46:47]
	s_cbranch_vccnz .LBB0_190
	s_add_i32 s4, s22, 3
	s_and_b32 s5, s4, 0xff
	s_mulk_i32 s5, 0xab
	s_bfe_u32 s5, s5, 0x70009
	s_mul_i32 s5, s5, 3
	s_sub_i32 s4, s4, s5
	s_and_b32 s4, s4, 0xff
	s_mul_i32 s4, s4, 0x8c00
	v_add_u32_e32 v66, s4, v76
	v_lshl_add_u32 v67, v106, 1, v66
	v_add3_u32 v66, v66, v77, v119
	s_cmp_eq_u32 s22, 28
	s_cbranch_scc0 .Lrv_b2_n0
	s_waitcnt vmcnt(2)
	s_branch .Lrv_b2_end
.Lrv_b2_n0:
	s_cmp_eq_u32 s22, 0
	s_cbranch_scc0 .Lrv_b2_n1
	s_waitcnt vmcnt(5)
	s_branch .Lrv_b2_end

.Lrv_b2_end:
	ds_write_b128 v67, v[6:9]
	ds_write_b128 v67, v[10:13] offset:9216
	ds_write_b128 v66, v[14:17] offset:18432
	ds_write_b128 v66, v[18:21] offset:18448
	s_branch .LBB0_190
